# GEMM unit setup: accumulator zero-init via 64 v_mov_b64 instead of 128 v_mov_b32
# baseline (speedup 1.0000x reference)
.LBB0_40:
	s_ashr_i32 s61, s60, 31
	s_lshl_b64 s[20:21], s[60:61], 21
	s_add_u32 s64, s24, s20
	s_addc_u32 s65, s25, s21
	s_ashr_i32 s63, s62, 31
	s_lshl_b64 s[20:21], s[62:63], 21
	v_readlane_b32 s42, v254, 54
	s_add_u32 s66, s42, s20
	v_readlane_b32 s20, v254, 62
	s_addc_u32 s67, s20, s21
	s_andn2_b64 vcc, exec, s[56:57]
	s_waitcnt lgkmcnt(0)
	v_mov_b64_e32 v[0:1], 0
	v_mov_b64_e32 v[2:3], 0
	v_mov_b64_e32 v[4:5], 0
	v_mov_b64_e32 v[6:7], 0
	v_mov_b64_e32 v[8:9], 0
	v_mov_b64_e32 v[10:11], 0
	v_mov_b64_e32 v[12:13], 0
	v_mov_b64_e32 v[14:15], 0
	v_mov_b64_e32 v[16:17], 0
	v_mov_b64_e32 v[18:19], 0
	v_mov_b64_e32 v[20:21], 0
	v_mov_b64_e32 v[22:23], 0
	v_mov_b64_e32 v[24:25], 0
	v_mov_b64_e32 v[26:27], 0
	v_mov_b64_e32 v[28:29], 0
	v_mov_b64_e32 v[30:31], 0
	v_mov_b64_e32 v[32:33], 0
	v_mov_b64_e32 v[34:35], 0
	v_mov_b64_e32 v[36:37], 0
	v_mov_b64_e32 v[38:39], 0
	v_mov_b64_e32 v[40:41], 0
	v_mov_b64_e32 v[42:43], 0
	v_mov_b64_e32 v[44:45], 0
	v_mov_b64_e32 v[46:47], 0
	v_mov_b64_e32 v[48:49], 0
	v_mov_b64_e32 v[50:51], 0
	v_mov_b64_e32 v[52:53], 0
	v_mov_b64_e32 v[54:55], 0
	v_mov_b64_e32 v[56:57], 0
	v_mov_b64_e32 v[58:59], 0
	v_mov_b64_e32 v[60:61], 0
	v_mov_b64_e32 v[62:63], 0
	v_mov_b64_e32 v[64:65], 0
	v_mov_b64_e32 v[66:67], 0
	v_mov_b64_e32 v[68:69], 0
	v_mov_b64_e32 v[70:71], 0
	v_mov_b64_e32 v[72:73], 0
	v_mov_b64_e32 v[74:75], 0
	v_mov_b64_e32 v[76:77], 0
	v_mov_b64_e32 v[78:79], 0
	v_mov_b64_e32 v[80:81], 0
	v_mov_b64_e32 v[82:83], 0
	v_mov_b64_e32 v[84:85], 0
	v_mov_b64_e32 v[86:87], 0
	v_mov_b64_e32 v[88:89], 0
	v_mov_b64_e32 v[90:91], 0
	v_mov_b64_e32 v[92:93], 0
	v_mov_b64_e32 v[94:95], 0
	v_mov_b64_e32 v[96:97], 0
	v_mov_b64_e32 v[98:99], 0
	v_mov_b64_e32 v[100:101], 0
	v_mov_b64_e32 v[102:103], 0
	v_mov_b64_e32 v[104:105], 0
	v_mov_b64_e32 v[106:107], 0
	v_mov_b64_e32 v[108:109], 0
	v_mov_b64_e32 v[110:111], 0
	v_mov_b64_e32 v[112:113], 0
	v_mov_b64_e32 v[114:115], 0
	v_mov_b64_e32 v[116:117], 0
	v_mov_b64_e32 v[118:119], 0
	v_mov_b64_e32 v[120:121], 0
	v_mov_b64_e32 v[122:123], 0
	v_mov_b64_e32 v[124:125], 0
	v_mov_b64_e32 v[126:127], 0
	s_cbranch_vccnz .LBB0_43
	s_and_b64 s[20:21], s[38:39], exec
	s_cselect_b32 s42, s65, s1
	s_cselect_b32 s43, s64, s0
	s_cselect_b32 s44, s67, s3
	s_cselect_b32 s45, s66, s2
	s_add_u32 s0, s0, 0x100080
	s_addc_u32 s1, s1, 0
	s_add_u32 s46, s2, 0x100
	s_addc_u32 s47, s3, 0
	s_mov_b32 s2, 0

.LBB0_88:
	s_ashr_i32 s61, s60, 31
	s_lshl_b64 s[20:21], s[60:61], 21
	s_add_u32 s64, s24, s20
	s_addc_u32 s65, s25, s21
	s_ashr_i32 s63, s62, 31
	s_lshl_b64 s[20:21], s[62:63], 21
	v_readlane_b32 s22, v254, 54
	s_add_u32 s66, s22, s20
	v_readlane_b32 s20, v254, 62
	s_addc_u32 s67, s20, s21
	s_andn2_b64 vcc, exec, s[42:43]
	s_waitcnt lgkmcnt(0)
	v_mov_b64_e32 v[0:1], 0
	v_mov_b64_e32 v[2:3], 0
	v_mov_b64_e32 v[4:5], 0
	v_mov_b64_e32 v[6:7], 0
	v_mov_b64_e32 v[8:9], 0
	v_mov_b64_e32 v[10:11], 0
	v_mov_b64_e32 v[12:13], 0
	v_mov_b64_e32 v[14:15], 0
	v_mov_b64_e32 v[16:17], 0
	v_mov_b64_e32 v[18:19], 0
	v_mov_b64_e32 v[20:21], 0
	v_mov_b64_e32 v[22:23], 0
	v_mov_b64_e32 v[24:25], 0
	v_mov_b64_e32 v[26:27], 0
	v_mov_b64_e32 v[28:29], 0
	v_mov_b64_e32 v[30:31], 0
	v_mov_b64_e32 v[32:33], 0
	v_mov_b64_e32 v[34:35], 0
	v_mov_b64_e32 v[36:37], 0
	v_mov_b64_e32 v[38:39], 0
	v_mov_b64_e32 v[40:41], 0
	v_mov_b64_e32 v[42:43], 0
	v_mov_b64_e32 v[44:45], 0
	v_mov_b64_e32 v[46:47], 0
	v_mov_b64_e32 v[48:49], 0
	v_mov_b64_e32 v[50:51], 0
	v_mov_b64_e32 v[52:53], 0
	v_mov_b64_e32 v[54:55], 0
	v_mov_b64_e32 v[56:57], 0
	v_mov_b64_e32 v[58:59], 0
	v_mov_b64_e32 v[60:61], 0
	v_mov_b64_e32 v[62:63], 0
	v_mov_b64_e32 v[64:65], 0
	v_mov_b64_e32 v[66:67], 0
	v_mov_b64_e32 v[68:69], 0
	v_mov_b64_e32 v[70:71], 0
	v_mov_b64_e32 v[72:73], 0
	v_mov_b64_e32 v[74:75], 0
	v_mov_b64_e32 v[76:77], 0
	v_mov_b64_e32 v[78:79], 0
	v_mov_b64_e32 v[80:81], 0
	v_mov_b64_e32 v[82:83], 0
	v_mov_b64_e32 v[84:85], 0
	v_mov_b64_e32 v[86:87], 0
	v_mov_b64_e32 v[88:89], 0
	v_mov_b64_e32 v[90:91], 0
	v_mov_b64_e32 v[92:93], 0
	v_mov_b64_e32 v[94:95], 0
	v_mov_b64_e32 v[96:97], 0
	v_mov_b64_e32 v[98:99], 0
	v_mov_b64_e32 v[100:101], 0
	v_mov_b64_e32 v[102:103], 0
	v_mov_b64_e32 v[104:105], 0
	v_mov_b64_e32 v[106:107], 0
	v_mov_b64_e32 v[108:109], 0
	v_mov_b64_e32 v[110:111], 0
	v_mov_b64_e32 v[112:113], 0
	v_mov_b64_e32 v[114:115], 0
	v_mov_b64_e32 v[116:117], 0
	v_mov_b64_e32 v[118:119], 0
	v_mov_b64_e32 v[120:121], 0
	v_mov_b64_e32 v[122:123], 0
	v_mov_b64_e32 v[124:125], 0
	v_mov_b64_e32 v[126:127], 0
	s_cbranch_vccnz .LBB0_92
	s_and_b64 s[20:21], s[38:39], exec
	s_mov_b64 s[68:69], s[42:43]
	s_cselect_b32 s22, s65, s1
	s_cselect_b32 s23, s64, s0
	s_cselect_b32 s34, s67, s3
	s_cselect_b32 s42, s66, s2
	s_add_u32 s0, s0, 0x100080
	s_addc_u32 s1, s1, 0
	s_add_u32 s43, s2, 0x100
	s_addc_u32 s44, s3, 0
	s_mov_b32 s2, 0

.LBB0_136:
	s_ashr_i32 s65, s64, 31
	s_lshl_b64 s[26:27], s[64:65], 19
	v_readlane_b32 s40, v254, 43
	v_readlane_b32 s41, v254, 44
	s_add_u32 s68, s40, s26
	s_addc_u32 s69, s41, s27
	s_ashr_i32 s67, s66, 31
	s_lshl_b64 s[26:27], s[66:67], 19
	s_add_u32 s70, s34, s26
	s_addc_u32 s71, s72, s27
	s_andn2_b64 vcc, exec, s[60:61]
	v_mov_b64_e32 v[0:1], 0
	v_mov_b64_e32 v[2:3], 0
	v_mov_b64_e32 v[4:5], 0
	v_mov_b64_e32 v[6:7], 0
	v_mov_b64_e32 v[8:9], 0
	v_mov_b64_e32 v[10:11], 0
	v_mov_b64_e32 v[12:13], 0
	v_mov_b64_e32 v[14:15], 0
	v_mov_b64_e32 v[16:17], 0
	v_mov_b64_e32 v[18:19], 0
	v_mov_b64_e32 v[20:21], 0
	v_mov_b64_e32 v[22:23], 0
	v_mov_b64_e32 v[24:25], 0
	v_mov_b64_e32 v[26:27], 0
	v_mov_b64_e32 v[28:29], 0
	v_mov_b64_e32 v[30:31], 0
	v_mov_b64_e32 v[32:33], 0
	v_mov_b64_e32 v[34:35], 0
	v_mov_b64_e32 v[36:37], 0
	v_mov_b64_e32 v[38:39], 0
	v_mov_b64_e32 v[40:41], 0
	v_mov_b64_e32 v[42:43], 0
	v_mov_b64_e32 v[44:45], 0
	v_mov_b64_e32 v[46:47], 0
	v_mov_b64_e32 v[48:49], 0
	v_mov_b64_e32 v[50:51], 0
	v_mov_b64_e32 v[52:53], 0
	v_mov_b64_e32 v[54:55], 0
	v_mov_b64_e32 v[56:57], 0
	v_mov_b64_e32 v[58:59], 0
	v_mov_b64_e32 v[60:61], 0
	v_mov_b64_e32 v[62:63], 0
	v_mov_b64_e32 v[80:81], 0
	v_mov_b64_e32 v[82:83], 0
	v_mov_b64_e32 v[84:85], 0
	v_mov_b64_e32 v[86:87], 0
	v_mov_b64_e32 v[104:105], 0
	v_mov_b64_e32 v[106:107], 0
	v_mov_b64_e32 v[108:109], 0
	v_mov_b64_e32 v[110:111], 0
	v_mov_b64_e32 v[112:113], 0
	v_mov_b64_e32 v[114:115], 0
	v_mov_b64_e32 v[116:117], 0
	v_mov_b64_e32 v[118:119], 0
	v_mov_b64_e32 v[120:121], 0
	v_mov_b64_e32 v[122:123], 0
	v_mov_b64_e32 v[124:125], 0
	v_mov_b64_e32 v[126:127], 0
	v_mov_b64_e32 v[128:129], 0
	v_mov_b64_e32 v[130:131], 0
	v_mov_b64_e32 v[132:133], 0
	v_mov_b64_e32 v[134:135], 0
	v_mov_b64_e32 v[136:137], 0
	v_mov_b64_e32 v[138:139], 0
	v_mov_b64_e32 v[140:141], 0
	v_mov_b64_e32 v[142:143], 0
	v_mov_b64_e32 v[144:145], 0
	v_mov_b64_e32 v[146:147], 0
	v_mov_b64_e32 v[148:149], 0
	v_mov_b64_e32 v[150:151], 0
	v_mov_b64_e32 v[152:153], 0
	v_mov_b64_e32 v[154:155], 0
	v_mov_b64_e32 v[156:157], 0
	v_mov_b64_e32 v[158:159], 0
	s_cbranch_vccnz .LBB0_139
	s_and_b64 s[26:27], s[38:39], exec
	s_cselect_b32 s1, s69, s21
	s_cselect_b32 s40, s68, s20
	s_cselect_b32 s41, s71, s23
	s_cselect_b32 s44, s70, s22
	s_add_u32 s20, s20, 0x40080
	s_addc_u32 s21, s21, 0
	s_add_u32 s45, s22, 0x100
	s_addc_u32 s53, s23, 0
	s_mov_b32 s22, 0

.LBB0_197:
	s_ashr_i32 s61, s60, 31
	s_lshl_b64 s[20:21], s[60:61], 19
	v_readlane_b32 s41, v254, 57
	s_add_u32 s64, s41, s20
	v_readlane_b32 s20, v254, 59
	s_addc_u32 s65, s20, s21
	s_ashr_i32 s63, s62, 31
	s_lshl_b64 s[20:21], s[62:63], 19
	s_add_u32 s66, s22, s20
	s_addc_u32 s67, s23, s21
	s_andn2_b64 vcc, exec, s[56:57]
	s_waitcnt lgkmcnt(0)
	v_mov_b64_e32 v[0:1], 0
	v_mov_b64_e32 v[2:3], 0
	v_mov_b64_e32 v[4:5], 0
	v_mov_b64_e32 v[6:7], 0
	v_mov_b64_e32 v[8:9], 0
	v_mov_b64_e32 v[10:11], 0
	v_mov_b64_e32 v[12:13], 0
	v_mov_b64_e32 v[14:15], 0
	v_mov_b64_e32 v[16:17], 0
	v_mov_b64_e32 v[18:19], 0
	v_mov_b64_e32 v[20:21], 0
	v_mov_b64_e32 v[22:23], 0
	v_mov_b64_e32 v[24:25], 0
	v_mov_b64_e32 v[26:27], 0
	v_mov_b64_e32 v[28:29], 0
	v_mov_b64_e32 v[30:31], 0
	v_mov_b64_e32 v[32:33], 0
	v_mov_b64_e32 v[34:35], 0
	v_mov_b64_e32 v[36:37], 0
	v_mov_b64_e32 v[38:39], 0
	v_mov_b64_e32 v[40:41], 0
	v_mov_b64_e32 v[42:43], 0
	v_mov_b64_e32 v[44:45], 0
	v_mov_b64_e32 v[46:47], 0
	v_mov_b64_e32 v[48:49], 0
	v_mov_b64_e32 v[50:51], 0
	v_mov_b64_e32 v[52:53], 0
	v_mov_b64_e32 v[54:55], 0
	v_mov_b64_e32 v[56:57], 0
	v_mov_b64_e32 v[58:59], 0
	v_mov_b64_e32 v[60:61], 0
	v_mov_b64_e32 v[62:63], 0
	v_mov_b64_e32 v[64:65], 0
	v_mov_b64_e32 v[66:67], 0
	v_mov_b64_e32 v[68:69], 0
	v_mov_b64_e32 v[70:71], 0
	v_mov_b64_e32 v[72:73], 0
	v_mov_b64_e32 v[74:75], 0
	v_mov_b64_e32 v[76:77], 0
	v_mov_b64_e32 v[78:79], 0
	v_mov_b64_e32 v[80:81], 0
	v_mov_b64_e32 v[82:83], 0
	v_mov_b64_e32 v[84:85], 0
	v_mov_b64_e32 v[86:87], 0
	v_mov_b64_e32 v[88:89], 0
	v_mov_b64_e32 v[90:91], 0
	v_mov_b64_e32 v[92:93], 0
	v_mov_b64_e32 v[94:95], 0
	v_mov_b64_e32 v[96:97], 0
	v_mov_b64_e32 v[98:99], 0
	v_mov_b64_e32 v[100:101], 0
	v_mov_b64_e32 v[102:103], 0
	v_mov_b64_e32 v[104:105], 0
	v_mov_b64_e32 v[106:107], 0
	v_mov_b64_e32 v[108:109], 0
	v_mov_b64_e32 v[110:111], 0
	v_mov_b64_e32 v[112:113], 0
	v_mov_b64_e32 v[114:115], 0
	v_mov_b64_e32 v[116:117], 0
	v_mov_b64_e32 v[118:119], 0
	v_mov_b64_e32 v[120:121], 0
	v_mov_b64_e32 v[122:123], 0
	v_mov_b64_e32 v[124:125], 0
	v_mov_b64_e32 v[126:127], 0
	s_cbranch_vccnz .LBB0_200
	s_and_b64 s[20:21], s[38:39], exec
	s_cselect_b32 s41, s65, s1
	s_cselect_b32 s42, s64, s0
	s_cselect_b32 s43, s67, s3
	s_cselect_b32 s44, s66, s2
	s_add_u32 s0, s0, 0x40080
	s_addc_u32 s1, s1, 0
	s_add_u32 s45, s2, 0x100
	s_addc_u32 s46, s3, 0
	s_mov_b32 s2, 0

.LBB0_248:
	s_andn2_b64 vcc, exec, s[20:21]
	v_mov_b64_e32 v[0:1], 0
	v_mov_b64_e32 v[2:3], 0
	v_mov_b64_e32 v[4:5], 0
	v_mov_b64_e32 v[6:7], 0
	v_mov_b64_e32 v[8:9], 0
	v_mov_b64_e32 v[10:11], 0
	v_mov_b64_e32 v[12:13], 0
	v_mov_b64_e32 v[14:15], 0
	v_mov_b64_e32 v[16:17], 0
	v_mov_b64_e32 v[18:19], 0
	v_mov_b64_e32 v[20:21], 0
	v_mov_b64_e32 v[22:23], 0
	v_mov_b64_e32 v[24:25], 0
	v_mov_b64_e32 v[26:27], 0
	v_mov_b64_e32 v[28:29], 0
	v_mov_b64_e32 v[30:31], 0
	v_mov_b64_e32 v[32:33], 0
	v_mov_b64_e32 v[34:35], 0
	v_mov_b64_e32 v[36:37], 0
	v_mov_b64_e32 v[38:39], 0
	v_mov_b64_e32 v[40:41], 0
	v_mov_b64_e32 v[42:43], 0
	v_mov_b64_e32 v[44:45], 0
	v_mov_b64_e32 v[46:47], 0
	v_mov_b64_e32 v[48:49], 0
	v_mov_b64_e32 v[50:51], 0
	v_mov_b64_e32 v[52:53], 0
	v_mov_b64_e32 v[54:55], 0
	v_mov_b64_e32 v[56:57], 0
	v_mov_b64_e32 v[58:59], 0
	v_mov_b64_e32 v[60:61], 0
	v_mov_b64_e32 v[62:63], 0
	v_mov_b64_e32 v[64:65], 0
	v_mov_b64_e32 v[66:67], 0
	v_mov_b64_e32 v[68:69], 0
	v_mov_b64_e32 v[70:71], 0
	v_mov_b64_e32 v[72:73], 0
	v_mov_b64_e32 v[74:75], 0
	v_mov_b64_e32 v[76:77], 0
	v_mov_b64_e32 v[78:79], 0
	v_mov_b64_e32 v[80:81], 0
	v_mov_b64_e32 v[82:83], 0
	v_mov_b64_e32 v[84:85], 0
	v_mov_b64_e32 v[86:87], 0
	v_mov_b64_e32 v[88:89], 0
	v_mov_b64_e32 v[90:91], 0
	v_mov_b64_e32 v[92:93], 0
	v_mov_b64_e32 v[94:95], 0
	v_mov_b64_e32 v[96:97], 0
	v_mov_b64_e32 v[98:99], 0
	v_mov_b64_e32 v[100:101], 0
	v_mov_b64_e32 v[102:103], 0
	v_mov_b64_e32 v[104:105], 0
	v_mov_b64_e32 v[106:107], 0
	v_mov_b64_e32 v[108:109], 0
	v_mov_b64_e32 v[110:111], 0
	v_mov_b64_e32 v[112:113], 0
	v_mov_b64_e32 v[114:115], 0
	v_mov_b64_e32 v[116:117], 0
	v_mov_b64_e32 v[118:119], 0
	v_mov_b64_e32 v[120:121], 0
	v_mov_b64_e32 v[122:123], 0
	v_mov_b64_e32 v[124:125], 0
	v_mov_b64_e32 v[126:127], 0
	s_cbranch_vccnz .LBB0_251
	s_add_u32 s0, s64, 0x40080
	s_addc_u32 s1, s65, 0
	s_add_u32 s3, s62, 0x100
	s_addc_u32 s27, s63, 0
	s_mov_b32 s41, 0

.LBB0_315:
	s_andn2_b64 vcc, exec, s[48:49]
	v_mov_b64_e32 v[0:1], 0
	v_mov_b64_e32 v[2:3], 0
	v_mov_b64_e32 v[4:5], 0
	v_mov_b64_e32 v[6:7], 0
	v_mov_b64_e32 v[8:9], 0
	v_mov_b64_e32 v[10:11], 0
	v_mov_b64_e32 v[12:13], 0
	v_mov_b64_e32 v[14:15], 0
	v_mov_b64_e32 v[16:17], 0
	v_mov_b64_e32 v[18:19], 0
	v_mov_b64_e32 v[20:21], 0
	v_mov_b64_e32 v[22:23], 0
	v_mov_b64_e32 v[24:25], 0
	v_mov_b64_e32 v[26:27], 0
	v_mov_b64_e32 v[28:29], 0
	v_mov_b64_e32 v[30:31], 0
	v_mov_b64_e32 v[32:33], 0
	v_mov_b64_e32 v[34:35], 0
	v_mov_b64_e32 v[36:37], 0
	v_mov_b64_e32 v[38:39], 0
	v_mov_b64_e32 v[40:41], 0
	v_mov_b64_e32 v[42:43], 0
	v_mov_b64_e32 v[44:45], 0
	v_mov_b64_e32 v[46:47], 0
	v_mov_b64_e32 v[48:49], 0
	v_mov_b64_e32 v[50:51], 0
	v_mov_b64_e32 v[52:53], 0
	v_mov_b64_e32 v[54:55], 0
	v_mov_b64_e32 v[56:57], 0
	v_mov_b64_e32 v[58:59], 0
	v_mov_b64_e32 v[60:61], 0
	v_mov_b64_e32 v[62:63], 0
	v_mov_b64_e32 v[64:65], 0
	v_mov_b64_e32 v[66:67], 0
	v_mov_b64_e32 v[68:69], 0
	v_mov_b64_e32 v[70:71], 0
	v_mov_b64_e32 v[72:73], 0
	v_mov_b64_e32 v[74:75], 0
	v_mov_b64_e32 v[76:77], 0
	v_mov_b64_e32 v[78:79], 0
	v_mov_b64_e32 v[80:81], 0
	v_mov_b64_e32 v[82:83], 0
	v_mov_b64_e32 v[84:85], 0
	v_mov_b64_e32 v[86:87], 0
	v_mov_b64_e32 v[88:89], 0
	v_mov_b64_e32 v[90:91], 0
	v_mov_b64_e32 v[92:93], 0
	v_mov_b64_e32 v[94:95], 0
	v_mov_b64_e32 v[96:97], 0
	v_mov_b64_e32 v[98:99], 0
	v_mov_b64_e32 v[100:101], 0
	v_mov_b64_e32 v[102:103], 0
	v_mov_b64_e32 v[104:105], 0
	v_mov_b64_e32 v[106:107], 0
	v_mov_b64_e32 v[108:109], 0
	v_mov_b64_e32 v[110:111], 0
	v_mov_b64_e32 v[112:113], 0
	v_mov_b64_e32 v[114:115], 0
	v_mov_b64_e32 v[116:117], 0
	v_mov_b64_e32 v[118:119], 0
	v_mov_b64_e32 v[120:121], 0
	v_mov_b64_e32 v[122:123], 0
	v_mov_b64_e32 v[124:125], 0
	v_mov_b64_e32 v[126:127], 0
	s_cbranch_vccnz .LBB0_318
	s_add_u32 s2, s2, 0x40080
	s_addc_u32 s3, s3, 0
	s_add_u32 s55, s20, 0x100
	s_addc_u32 s57, s21, 0
	s_mov_b32 s20, 0

.LBB0_376:
	s_ashr_i32 s63, s62, 31
	s_lshl_b64 s[26:27], s[62:63], 19
	v_readlane_b32 s40, v254, 43
	v_readlane_b32 s41, v254, 44
	s_add_u32 s66, s40, s26
	s_addc_u32 s67, s41, s27
	s_ashr_i32 s65, s64, 31
	s_lshl_b64 s[26:27], s[64:65], 19
	s_add_u32 s68, s34, s26
	s_addc_u32 s69, s42, s27
	s_andn2_b64 vcc, exec, s[58:59]
	v_mov_b64_e32 v[0:1], 0
	v_mov_b64_e32 v[2:3], 0
	v_mov_b64_e32 v[4:5], 0
	v_mov_b64_e32 v[6:7], 0
	v_mov_b64_e32 v[8:9], 0
	v_mov_b64_e32 v[10:11], 0
	v_mov_b64_e32 v[12:13], 0
	v_mov_b64_e32 v[14:15], 0
	v_mov_b64_e32 v[16:17], 0
	v_mov_b64_e32 v[18:19], 0
	v_mov_b64_e32 v[20:21], 0
	v_mov_b64_e32 v[22:23], 0
	v_mov_b64_e32 v[24:25], 0
	v_mov_b64_e32 v[26:27], 0
	v_mov_b64_e32 v[28:29], 0
	v_mov_b64_e32 v[30:31], 0
	v_mov_b64_e32 v[32:33], 0
	v_mov_b64_e32 v[34:35], 0
	v_mov_b64_e32 v[36:37], 0
	v_mov_b64_e32 v[38:39], 0
	v_mov_b64_e32 v[40:41], 0
	v_mov_b64_e32 v[42:43], 0
	v_mov_b64_e32 v[44:45], 0
	v_mov_b64_e32 v[46:47], 0
	v_mov_b64_e32 v[48:49], 0
	v_mov_b64_e32 v[50:51], 0
	v_mov_b64_e32 v[52:53], 0
	v_mov_b64_e32 v[54:55], 0
	v_mov_b64_e32 v[56:57], 0
	v_mov_b64_e32 v[58:59], 0
	v_mov_b64_e32 v[60:61], 0
	v_mov_b64_e32 v[62:63], 0
	v_mov_b64_e32 v[64:65], 0
	v_mov_b64_e32 v[66:67], 0
	v_mov_b64_e32 v[68:69], 0
	v_mov_b64_e32 v[70:71], 0
	v_mov_b64_e32 v[80:81], 0
	v_mov_b64_e32 v[82:83], 0
	v_mov_b64_e32 v[92:93], 0
	v_mov_b64_e32 v[94:95], 0
	v_mov_b64_e32 v[112:113], 0
	v_mov_b64_e32 v[114:115], 0
	v_mov_b64_e32 v[116:117], 0
	v_mov_b64_e32 v[118:119], 0
	v_mov_b64_e32 v[120:121], 0
	v_mov_b64_e32 v[122:123], 0
	v_mov_b64_e32 v[124:125], 0
	v_mov_b64_e32 v[126:127], 0
	v_mov_b64_e32 v[128:129], 0
	v_mov_b64_e32 v[130:131], 0
	v_mov_b64_e32 v[132:133], 0
	v_mov_b64_e32 v[134:135], 0
	v_mov_b64_e32 v[136:137], 0
	v_mov_b64_e32 v[138:139], 0
	v_mov_b64_e32 v[140:141], 0
	v_mov_b64_e32 v[142:143], 0
	v_mov_b64_e32 v[144:145], 0
	v_mov_b64_e32 v[146:147], 0
	v_mov_b64_e32 v[148:149], 0
	v_mov_b64_e32 v[150:151], 0
	v_mov_b64_e32 v[152:153], 0
	v_mov_b64_e32 v[154:155], 0
	v_mov_b64_e32 v[156:157], 0
	v_mov_b64_e32 v[158:159], 0
	s_cbranch_vccnz .LBB0_379
	s_and_b64 s[26:27], s[38:39], exec
	s_cselect_b32 s1, s67, s21
	s_cselect_b32 s40, s66, s20
	s_cselect_b32 s41, s69, s23
	s_cselect_b32 s44, s68, s22
	s_add_u32 s20, s20, 0x40080
	s_addc_u32 s21, s21, 0
	s_add_u32 s45, s22, 0x100
	s_addc_u32 s63, s23, 0
	s_mov_b32 s22, 0

.LBB0_442:
	s_ashr_i32 s51, s50, 31
	s_lshl_b64 s[20:21], s[50:51], 19
	v_readlane_b32 s42, v254, 57
	v_readlane_b32 s43, v254, 58
	s_add_u32 s54, s42, s20
	s_addc_u32 s55, s43, s21
	s_ashr_i32 s53, s52, 31
	s_lshl_b64 s[20:21], s[52:53], 19
	s_add_u32 s56, s34, s20
	s_addc_u32 s57, s60, s21
	s_andn2_b64 vcc, exec, s[46:47]
	s_waitcnt lgkmcnt(0)
	v_mov_b64_e32 v[0:1], 0
	v_mov_b64_e32 v[2:3], 0
	v_mov_b64_e32 v[4:5], 0
	v_mov_b64_e32 v[6:7], 0
	v_mov_b64_e32 v[8:9], 0
	v_mov_b64_e32 v[10:11], 0
	v_mov_b64_e32 v[12:13], 0
	v_mov_b64_e32 v[14:15], 0
	v_mov_b64_e32 v[16:17], 0
	v_mov_b64_e32 v[18:19], 0
	v_mov_b64_e32 v[20:21], 0
	v_mov_b64_e32 v[22:23], 0
	v_mov_b64_e32 v[24:25], 0
	v_mov_b64_e32 v[26:27], 0
	v_mov_b64_e32 v[28:29], 0
	v_mov_b64_e32 v[30:31], 0
	v_mov_b64_e32 v[32:33], 0
	v_mov_b64_e32 v[34:35], 0
	v_mov_b64_e32 v[36:37], 0
	v_mov_b64_e32 v[38:39], 0
	v_mov_b64_e32 v[40:41], 0
	v_mov_b64_e32 v[42:43], 0
	v_mov_b64_e32 v[44:45], 0
	v_mov_b64_e32 v[46:47], 0
	v_mov_b64_e32 v[48:49], 0
	v_mov_b64_e32 v[50:51], 0
	v_mov_b64_e32 v[52:53], 0
	v_mov_b64_e32 v[54:55], 0
	v_mov_b64_e32 v[56:57], 0
	v_mov_b64_e32 v[58:59], 0
	v_mov_b64_e32 v[60:61], 0
	v_mov_b64_e32 v[62:63], 0
	v_mov_b64_e32 v[64:65], 0
	v_mov_b64_e32 v[66:67], 0
	v_mov_b64_e32 v[68:69], 0
	v_mov_b64_e32 v[70:71], 0
	v_mov_b64_e32 v[72:73], 0
	v_mov_b64_e32 v[74:75], 0
	v_mov_b64_e32 v[76:77], 0
	v_mov_b64_e32 v[78:79], 0
	v_mov_b64_e32 v[80:81], 0
	v_mov_b64_e32 v[82:83], 0
	v_mov_b64_e32 v[84:85], 0
	v_mov_b64_e32 v[86:87], 0
	v_mov_b64_e32 v[88:89], 0
	v_mov_b64_e32 v[90:91], 0
	v_mov_b64_e32 v[92:93], 0
	v_mov_b64_e32 v[94:95], 0
	v_mov_b64_e32 v[96:97], 0
	v_mov_b64_e32 v[98:99], 0
	v_mov_b64_e32 v[100:101], 0
	v_mov_b64_e32 v[102:103], 0
	v_mov_b64_e32 v[104:105], 0
	v_mov_b64_e32 v[106:107], 0
	v_mov_b64_e32 v[108:109], 0
	v_mov_b64_e32 v[110:111], 0
	v_mov_b64_e32 v[112:113], 0
	v_mov_b64_e32 v[114:115], 0
	v_mov_b64_e32 v[116:117], 0
	v_mov_b64_e32 v[118:119], 0
	v_mov_b64_e32 v[120:121], 0
	v_mov_b64_e32 v[122:123], 0
	v_mov_b64_e32 v[124:125], 0
	v_mov_b64_e32 v[126:127], 0
	s_cbranch_vccnz .LBB0_445
	s_and_b64 s[20:21], s[38:39], exec
	s_cselect_b32 s41, s55, s1
	s_cselect_b32 s42, s54, s0
	s_cselect_b32 s43, s57, s3
	s_cselect_b32 s51, s56, s2
	s_add_u32 s0, s0, 0x40080
	s_addc_u32 s1, s1, 0
	s_add_u32 s53, s2, 0x100
	s_addc_u32 s58, s3, 0
	s_mov_b32 s2, 0

.LBB0_489:
	s_ashr_i32 s49, s48, 31
	s_lshl_b64 s[22:23], s[48:49], 19
	v_readlane_b32 s40, v254, 57
	v_readlane_b32 s41, v254, 58
	s_add_u32 s52, s40, s22
	s_addc_u32 s53, s41, s23
	s_ashr_i32 s51, s50, 31
	s_lshl_b64 s[22:23], s[50:51], 19
	s_add_u32 s54, s34, s22
	s_addc_u32 s55, s60, s23
	s_andn2_b64 vcc, exec, s[44:45]
	s_waitcnt lgkmcnt(0)
	v_mov_b64_e32 v[0:1], 0
	v_mov_b64_e32 v[2:3], 0
	v_mov_b64_e32 v[4:5], 0
	v_mov_b64_e32 v[6:7], 0
	v_mov_b64_e32 v[8:9], 0
	v_mov_b64_e32 v[10:11], 0
	v_mov_b64_e32 v[12:13], 0
	v_mov_b64_e32 v[14:15], 0
	v_mov_b64_e32 v[16:17], 0
	v_mov_b64_e32 v[18:19], 0
	v_mov_b64_e32 v[20:21], 0
	v_mov_b64_e32 v[22:23], 0
	v_mov_b64_e32 v[24:25], 0
	v_mov_b64_e32 v[26:27], 0
	v_mov_b64_e32 v[28:29], 0
	v_mov_b64_e32 v[30:31], 0
	v_mov_b64_e32 v[32:33], 0
	v_mov_b64_e32 v[34:35], 0
	v_mov_b64_e32 v[36:37], 0
	v_mov_b64_e32 v[38:39], 0
	v_mov_b64_e32 v[40:41], 0
	v_mov_b64_e32 v[42:43], 0
	v_mov_b64_e32 v[44:45], 0
	v_mov_b64_e32 v[46:47], 0
	v_mov_b64_e32 v[48:49], 0
	v_mov_b64_e32 v[50:51], 0
	v_mov_b64_e32 v[52:53], 0
	v_mov_b64_e32 v[54:55], 0
	v_mov_b64_e32 v[56:57], 0
	v_mov_b64_e32 v[58:59], 0
	v_mov_b64_e32 v[60:61], 0
	v_mov_b64_e32 v[62:63], 0
	v_mov_b64_e32 v[64:65], 0
	v_mov_b64_e32 v[66:67], 0
	v_mov_b64_e32 v[68:69], 0
	v_mov_b64_e32 v[70:71], 0
	v_mov_b64_e32 v[72:73], 0
	v_mov_b64_e32 v[74:75], 0
	v_mov_b64_e32 v[76:77], 0
	v_mov_b64_e32 v[78:79], 0
	v_mov_b64_e32 v[80:81], 0
	v_mov_b64_e32 v[82:83], 0
	v_mov_b64_e32 v[84:85], 0
	v_mov_b64_e32 v[86:87], 0
	v_mov_b64_e32 v[88:89], 0
	v_mov_b64_e32 v[90:91], 0
	v_mov_b64_e32 v[92:93], 0
	v_mov_b64_e32 v[94:95], 0
	v_mov_b64_e32 v[96:97], 0
	v_mov_b64_e32 v[98:99], 0
	v_mov_b64_e32 v[100:101], 0
	v_mov_b64_e32 v[102:103], 0
	v_mov_b64_e32 v[104:105], 0
	v_mov_b64_e32 v[106:107], 0
	v_mov_b64_e32 v[108:109], 0
	v_mov_b64_e32 v[110:111], 0
	v_mov_b64_e32 v[112:113], 0
	v_mov_b64_e32 v[114:115], 0
	v_mov_b64_e32 v[116:117], 0
	v_mov_b64_e32 v[118:119], 0
	v_mov_b64_e32 v[120:121], 0
	v_mov_b64_e32 v[122:123], 0
	v_mov_b64_e32 v[124:125], 0
	v_mov_b64_e32 v[126:127], 0
	s_cbranch_vccnz .LBB0_492
	s_and_b64 s[22:23], s[38:39], exec
	s_cselect_b32 s1, s53, s3
	s_cselect_b32 s25, s52, s2
	s_cselect_b32 s40, s55, s21
	s_cselect_b32 s41, s54, s20
	s_add_u32 s2, s2, 0x40080
	s_addc_u32 s3, s3, 0
	s_add_u32 s49, s20, 0x100
	s_addc_u32 s51, s21, 0
	s_mov_b32 s20, 0

.LBB0_535:
	s_ashr_i32 s47, s46, 31
	s_lshl_b64 s[22:23], s[46:47], 19
	s_add_u32 s48, s52, s22
	s_addc_u32 s49, s53, s23
	s_andn2_b64 vcc, exec, s[42:43]
	v_mov_b64_e32 v[0:1], 0
	v_mov_b64_e32 v[2:3], 0
	v_mov_b64_e32 v[4:5], 0
	v_mov_b64_e32 v[6:7], 0
	v_mov_b64_e32 v[8:9], 0
	v_mov_b64_e32 v[10:11], 0
	v_mov_b64_e32 v[12:13], 0
	v_mov_b64_e32 v[14:15], 0
	v_mov_b64_e32 v[16:17], 0
	v_mov_b64_e32 v[18:19], 0
	v_mov_b64_e32 v[20:21], 0
	v_mov_b64_e32 v[22:23], 0
	v_mov_b64_e32 v[24:25], 0
	v_mov_b64_e32 v[26:27], 0
	v_mov_b64_e32 v[28:29], 0
	v_mov_b64_e32 v[30:31], 0
	v_mov_b64_e32 v[32:33], 0
	v_mov_b64_e32 v[34:35], 0
	v_mov_b64_e32 v[36:37], 0
	v_mov_b64_e32 v[38:39], 0
	v_mov_b64_e32 v[40:41], 0
	v_mov_b64_e32 v[42:43], 0
	v_mov_b64_e32 v[44:45], 0
	v_mov_b64_e32 v[46:47], 0
	v_mov_b64_e32 v[48:49], 0
	v_mov_b64_e32 v[50:51], 0
	v_mov_b64_e32 v[52:53], 0
	v_mov_b64_e32 v[54:55], 0
	v_mov_b64_e32 v[56:57], 0
	v_mov_b64_e32 v[58:59], 0
	v_mov_b64_e32 v[60:61], 0
	v_mov_b64_e32 v[62:63], 0
	v_mov_b64_e32 v[64:65], 0
	v_mov_b64_e32 v[66:67], 0
	v_mov_b64_e32 v[68:69], 0
	v_mov_b64_e32 v[70:71], 0
	v_mov_b64_e32 v[72:73], 0
	v_mov_b64_e32 v[74:75], 0
	v_mov_b64_e32 v[76:77], 0
	v_mov_b64_e32 v[78:79], 0
	v_mov_b64_e32 v[80:81], 0
	v_mov_b64_e32 v[82:83], 0
	v_mov_b64_e32 v[84:85], 0
	v_mov_b64_e32 v[86:87], 0
	v_mov_b64_e32 v[88:89], 0
	v_mov_b64_e32 v[90:91], 0
	v_mov_b64_e32 v[92:93], 0
	v_mov_b64_e32 v[94:95], 0
	v_mov_b64_e32 v[96:97], 0
	v_mov_b64_e32 v[98:99], 0
	v_mov_b64_e32 v[100:101], 0
	v_mov_b64_e32 v[102:103], 0
	v_mov_b64_e32 v[104:105], 0
	v_mov_b64_e32 v[106:107], 0
	v_mov_b64_e32 v[108:109], 0
	v_mov_b64_e32 v[110:111], 0
	v_mov_b64_e32 v[112:113], 0
	v_mov_b64_e32 v[114:115], 0
	v_mov_b64_e32 v[116:117], 0
	v_mov_b64_e32 v[118:119], 0
	v_mov_b64_e32 v[120:121], 0
	v_mov_b64_e32 v[122:123], 0
	v_mov_b64_e32 v[124:125], 0
	v_mov_b64_e32 v[126:127], 0
	s_cbranch_vccnz .LBB0_539
	s_and_b64 s[22:23], s[38:39], exec
	s_cselect_b32 s3, s49, s21
	s_cselect_b32 s47, s48, s20
	s_add_u32 s66, s20, 0x100
	s_addc_u32 s67, s21, 0
	s_add_u32 s20, s20, 0x40080
	s_addc_u32 s21, s21, 0
	v_lshl_add_u64 v[138:139], s[20:21], 0, v[134:135]
	v_lshl_add_u64 v[140:141], s[20:21], 0, v[136:137]
	s_mov_b32 s26, 0
	s_mov_b64 s[20:21], 0

.LBB0_572:
	s_ashr_i32 s43, s42, 31
	s_ashr_i32 s45, s44, 31
	s_lshl_b64 s[46:47], s[44:45], 18
	s_lshl_b64 s[48:49], s[42:43], 22
	s_add_u32 s3, s78, s48
	s_addc_u32 s21, s79, s49
	s_add_u32 s46, s3, s46
	s_addc_u32 s47, s21, s47
	s_ashr_i32 s3, s67, 31
	s_add_u32 s48, s67, s42
	s_addc_u32 s49, s3, s43
	s_lshl_b64 s[48:49], s[48:49], 18
	s_add_u32 s48, s52, s48
	s_addc_u32 s49, s53, s49
	s_andn2_b64 vcc, exec, s[24:25]
	v_mov_b64_e32 v[0:1], 0
	v_mov_b64_e32 v[2:3], 0
	v_mov_b64_e32 v[4:5], 0
	v_mov_b64_e32 v[6:7], 0
	v_mov_b64_e32 v[8:9], 0
	v_mov_b64_e32 v[10:11], 0
	v_mov_b64_e32 v[12:13], 0
	v_mov_b64_e32 v[14:15], 0
	v_mov_b64_e32 v[16:17], 0
	v_mov_b64_e32 v[18:19], 0
	v_mov_b64_e32 v[20:21], 0
	v_mov_b64_e32 v[22:23], 0
	v_mov_b64_e32 v[24:25], 0
	v_mov_b64_e32 v[26:27], 0
	v_mov_b64_e32 v[28:29], 0
	v_mov_b64_e32 v[30:31], 0
	v_mov_b64_e32 v[32:33], 0
	v_mov_b64_e32 v[34:35], 0
	v_mov_b64_e32 v[36:37], 0
	v_mov_b64_e32 v[38:39], 0
	v_mov_b64_e32 v[40:41], 0
	v_mov_b64_e32 v[42:43], 0
	v_mov_b64_e32 v[44:45], 0
	v_mov_b64_e32 v[46:47], 0
	v_mov_b64_e32 v[48:49], 0
	v_mov_b64_e32 v[50:51], 0
	v_mov_b64_e32 v[52:53], 0
	v_mov_b64_e32 v[54:55], 0
	v_mov_b64_e32 v[56:57], 0
	v_mov_b64_e32 v[58:59], 0
	v_mov_b64_e32 v[60:61], 0
	v_mov_b64_e32 v[62:63], 0
	v_mov_b64_e32 v[64:65], 0
	v_mov_b64_e32 v[66:67], 0
	v_mov_b64_e32 v[68:69], 0
	v_mov_b64_e32 v[70:71], 0
	v_mov_b64_e32 v[72:73], 0
	v_mov_b64_e32 v[74:75], 0
	v_mov_b64_e32 v[76:77], 0
	v_mov_b64_e32 v[78:79], 0
	v_mov_b64_e32 v[80:81], 0
	v_mov_b64_e32 v[82:83], 0
	v_mov_b64_e32 v[84:85], 0
	v_mov_b64_e32 v[86:87], 0
	v_mov_b64_e32 v[88:89], 0
	v_mov_b64_e32 v[90:91], 0
	v_mov_b64_e32 v[92:93], 0
	v_mov_b64_e32 v[94:95], 0
	v_mov_b64_e32 v[96:97], 0
	v_mov_b64_e32 v[98:99], 0
	v_mov_b64_e32 v[100:101], 0
	v_mov_b64_e32 v[102:103], 0
	v_mov_b64_e32 v[104:105], 0
	v_mov_b64_e32 v[106:107], 0
	v_mov_b64_e32 v[108:109], 0
	v_mov_b64_e32 v[110:111], 0
	v_mov_b64_e32 v[112:113], 0
	v_mov_b64_e32 v[114:115], 0
	v_mov_b64_e32 v[116:117], 0
	v_mov_b64_e32 v[118:119], 0
	v_mov_b64_e32 v[120:121], 0
	v_mov_b64_e32 v[122:123], 0
	v_mov_b64_e32 v[124:125], 0
	v_mov_b64_e32 v[126:127], 0
	s_cbranch_vccnz .LBB0_575
	s_and_b64 s[50:51], s[38:39], exec
	s_cselect_b32 s3, s47, s23
	s_cselect_b32 s21, s46, s22
	s_cselect_b32 s43, s49, s27
	s_cselect_b32 s45, s48, s26
	s_add_u32 s22, s22, 0x20080
	s_addc_u32 s23, s23, 0
	s_add_u32 s68, s26, 0x100
	s_addc_u32 s69, s27, 0
	s_mov_b32 s26, 0

.LBB0_628:
	s_andn2_b64 vcc, exec, s[20:21]
	v_mov_b64_e32 v[0:1], 0
	v_mov_b64_e32 v[2:3], 0
	v_mov_b64_e32 v[4:5], 0
	v_mov_b64_e32 v[6:7], 0
	v_mov_b64_e32 v[8:9], 0
	v_mov_b64_e32 v[10:11], 0
	v_mov_b64_e32 v[12:13], 0
	v_mov_b64_e32 v[14:15], 0
	v_mov_b64_e32 v[16:17], 0
	v_mov_b64_e32 v[18:19], 0
	v_mov_b64_e32 v[20:21], 0
	v_mov_b64_e32 v[22:23], 0
	v_mov_b64_e32 v[24:25], 0
	v_mov_b64_e32 v[26:27], 0
	v_mov_b64_e32 v[28:29], 0
	v_mov_b64_e32 v[30:31], 0
	v_mov_b64_e32 v[32:33], 0
	v_mov_b64_e32 v[34:35], 0
	v_mov_b64_e32 v[36:37], 0
	v_mov_b64_e32 v[38:39], 0
	v_mov_b64_e32 v[40:41], 0
	v_mov_b64_e32 v[42:43], 0
	v_mov_b64_e32 v[44:45], 0
	v_mov_b64_e32 v[46:47], 0
	v_mov_b64_e32 v[48:49], 0
	v_mov_b64_e32 v[50:51], 0
	v_mov_b64_e32 v[52:53], 0
	v_mov_b64_e32 v[54:55], 0
	v_mov_b64_e32 v[56:57], 0
	v_mov_b64_e32 v[58:59], 0
	v_mov_b64_e32 v[60:61], 0
	v_mov_b64_e32 v[62:63], 0
	v_mov_b64_e32 v[64:65], 0
	v_mov_b64_e32 v[66:67], 0
	v_mov_b64_e32 v[68:69], 0
	v_mov_b64_e32 v[70:71], 0
	v_mov_b64_e32 v[72:73], 0
	v_mov_b64_e32 v[74:75], 0
	v_mov_b64_e32 v[76:77], 0
	v_mov_b64_e32 v[78:79], 0
	v_mov_b64_e32 v[80:81], 0
	v_mov_b64_e32 v[82:83], 0
	v_mov_b64_e32 v[84:85], 0
	v_mov_b64_e32 v[86:87], 0
	v_mov_b64_e32 v[88:89], 0
	v_mov_b64_e32 v[90:91], 0
	v_mov_b64_e32 v[92:93], 0
	v_mov_b64_e32 v[94:95], 0
	v_mov_b64_e32 v[96:97], 0
	v_mov_b64_e32 v[98:99], 0
	v_mov_b64_e32 v[100:101], 0
	v_mov_b64_e32 v[102:103], 0
	v_mov_b64_e32 v[104:105], 0
	v_mov_b64_e32 v[106:107], 0
	v_mov_b64_e32 v[108:109], 0
	v_mov_b64_e32 v[110:111], 0
	v_mov_b64_e32 v[112:113], 0
	v_mov_b64_e32 v[114:115], 0
	v_mov_b64_e32 v[116:117], 0
	v_mov_b64_e32 v[118:119], 0
	v_mov_b64_e32 v[120:121], 0
	v_mov_b64_e32 v[122:123], 0
	v_mov_b64_e32 v[124:125], 0
	v_mov_b64_e32 v[126:127], 0
	s_cbranch_vccnz .LBB0_631
	s_add_u32 s0, s50, 0x20080
	s_addc_u32 s1, s51, 0
	s_add_u32 s3, s48, 0x100
	s_addc_u32 s27, s49, 0
	s_mov_b32 s41, 0

.LBB0_851:
	s_ashr_i32 s53, s52, 31
	s_lshl_b64 s[26:27], s[52:53], 19
	v_readlane_b32 s40, v254, 43
	v_readlane_b32 s41, v254, 44
	s_add_u32 s56, s40, s26
	s_addc_u32 s57, s41, s27
	s_ashr_i32 s55, s54, 31
	s_lshl_b64 s[26:27], s[54:55], 19
	v_readlane_b32 s1, v254, 41
	s_add_u32 s58, s1, s26
	v_readlane_b32 s1, v254, 42
	s_addc_u32 s59, s1, s27
	s_andn2_b64 vcc, exec, s[48:49]
	v_mov_b64_e32 v[0:1], 0
	v_mov_b64_e32 v[2:3], 0
	v_mov_b64_e32 v[4:5], 0
	v_mov_b64_e32 v[6:7], 0
	v_mov_b64_e32 v[8:9], 0
	v_mov_b64_e32 v[10:11], 0
	v_mov_b64_e32 v[12:13], 0
	v_mov_b64_e32 v[14:15], 0
	v_mov_b64_e32 v[16:17], 0
	v_mov_b64_e32 v[18:19], 0
	v_mov_b64_e32 v[20:21], 0
	v_mov_b64_e32 v[22:23], 0
	v_mov_b64_e32 v[24:25], 0
	v_mov_b64_e32 v[26:27], 0
	v_mov_b64_e32 v[28:29], 0
	v_mov_b64_e32 v[30:31], 0
	v_mov_b64_e32 v[32:33], 0
	v_mov_b64_e32 v[34:35], 0
	v_mov_b64_e32 v[36:37], 0
	v_mov_b64_e32 v[38:39], 0
	v_mov_b64_e32 v[40:41], 0
	v_mov_b64_e32 v[42:43], 0
	v_mov_b64_e32 v[44:45], 0
	v_mov_b64_e32 v[46:47], 0
	v_mov_b64_e32 v[48:49], 0
	v_mov_b64_e32 v[50:51], 0
	v_mov_b64_e32 v[52:53], 0
	v_mov_b64_e32 v[54:55], 0
	v_mov_b64_e32 v[56:57], 0
	v_mov_b64_e32 v[58:59], 0
	v_mov_b64_e32 v[60:61], 0
	v_mov_b64_e32 v[62:63], 0
	v_mov_b64_e32 v[64:65], 0
	v_mov_b64_e32 v[66:67], 0
	v_mov_b64_e32 v[68:69], 0
	v_mov_b64_e32 v[70:71], 0
	v_mov_b64_e32 v[72:73], 0
	v_mov_b64_e32 v[74:75], 0
	v_mov_b64_e32 v[76:77], 0
	v_mov_b64_e32 v[78:79], 0
	v_mov_b64_e32 v[112:113], 0
	v_mov_b64_e32 v[114:115], 0
	v_mov_b64_e32 v[116:117], 0
	v_mov_b64_e32 v[118:119], 0
	v_mov_b64_e32 v[120:121], 0
	v_mov_b64_e32 v[122:123], 0
	v_mov_b64_e32 v[124:125], 0
	v_mov_b64_e32 v[126:127], 0
	v_mov_b64_e32 v[128:129], 0
	v_mov_b64_e32 v[130:131], 0
	v_mov_b64_e32 v[132:133], 0
	v_mov_b64_e32 v[134:135], 0
	v_mov_b64_e32 v[136:137], 0
	v_mov_b64_e32 v[138:139], 0
	v_mov_b64_e32 v[140:141], 0
	v_mov_b64_e32 v[142:143], 0
	v_mov_b64_e32 v[144:145], 0
	v_mov_b64_e32 v[146:147], 0
	v_mov_b64_e32 v[148:149], 0
	v_mov_b64_e32 v[150:151], 0
	v_mov_b64_e32 v[152:153], 0
	v_mov_b64_e32 v[154:155], 0
	v_mov_b64_e32 v[156:157], 0
	v_mov_b64_e32 v[158:159], 0
	s_cbranch_vccnz .LBB0_854
	s_and_b64 s[26:27], s[38:39], exec
	s_cselect_b32 s1, s57, s21
	s_cselect_b32 s40, s56, s20
	s_cselect_b32 s41, s59, s23
	s_cselect_b32 s53, s58, s22
	s_add_u32 s20, s20, 0x40080
	s_addc_u32 s21, s21, 0
	s_add_u32 s55, s22, 0x100
	s_addc_u32 s71, s23, 0
	s_mov_b32 s22, 0

.LBB0_914:
	s_ashr_i32 s47, s46, 31
	s_lshl_b64 s[50:51], s[46:47], 19
	s_add_u32 s50, s34, s50
	s_addc_u32 s51, s60, s51
	s_andn2_b64 vcc, exec, s[20:21]
	v_mov_b64_e32 v[0:1], 0
	v_mov_b64_e32 v[2:3], 0
	v_mov_b64_e32 v[4:5], 0
	v_mov_b64_e32 v[6:7], 0
	v_mov_b64_e32 v[8:9], 0
	v_mov_b64_e32 v[10:11], 0
	v_mov_b64_e32 v[12:13], 0
	v_mov_b64_e32 v[14:15], 0
	v_mov_b64_e32 v[16:17], 0
	v_mov_b64_e32 v[18:19], 0
	v_mov_b64_e32 v[20:21], 0
	v_mov_b64_e32 v[22:23], 0
	v_mov_b64_e32 v[24:25], 0
	v_mov_b64_e32 v[26:27], 0
	v_mov_b64_e32 v[28:29], 0
	v_mov_b64_e32 v[30:31], 0
	v_mov_b64_e32 v[32:33], 0
	v_mov_b64_e32 v[34:35], 0
	v_mov_b64_e32 v[36:37], 0
	v_mov_b64_e32 v[38:39], 0
	v_mov_b64_e32 v[40:41], 0
	v_mov_b64_e32 v[42:43], 0
	v_mov_b64_e32 v[44:45], 0
	v_mov_b64_e32 v[46:47], 0
	v_mov_b64_e32 v[48:49], 0
	v_mov_b64_e32 v[50:51], 0
	v_mov_b64_e32 v[52:53], 0
	v_mov_b64_e32 v[54:55], 0
	v_mov_b64_e32 v[56:57], 0
	v_mov_b64_e32 v[58:59], 0
	v_mov_b64_e32 v[60:61], 0
	v_mov_b64_e32 v[62:63], 0
	v_mov_b64_e32 v[64:65], 0
	v_mov_b64_e32 v[66:67], 0
	v_mov_b64_e32 v[68:69], 0
	v_mov_b64_e32 v[70:71], 0
	v_mov_b64_e32 v[72:73], 0
	v_mov_b64_e32 v[74:75], 0
	v_mov_b64_e32 v[76:77], 0
	v_mov_b64_e32 v[78:79], 0
	v_mov_b64_e32 v[80:81], 0
	v_mov_b64_e32 v[82:83], 0
	v_mov_b64_e32 v[84:85], 0
	v_mov_b64_e32 v[86:87], 0
	v_mov_b64_e32 v[88:89], 0
	v_mov_b64_e32 v[90:91], 0
	v_mov_b64_e32 v[92:93], 0
	v_mov_b64_e32 v[94:95], 0
	v_mov_b64_e32 v[96:97], 0
	v_mov_b64_e32 v[98:99], 0
	v_mov_b64_e32 v[100:101], 0
	v_mov_b64_e32 v[102:103], 0
	v_mov_b64_e32 v[104:105], 0
	v_mov_b64_e32 v[106:107], 0
	v_mov_b64_e32 v[108:109], 0
	v_mov_b64_e32 v[110:111], 0
	v_mov_b64_e32 v[112:113], 0
	v_mov_b64_e32 v[114:115], 0
	v_mov_b64_e32 v[116:117], 0
	v_mov_b64_e32 v[118:119], 0
	v_mov_b64_e32 v[120:121], 0
	v_mov_b64_e32 v[122:123], 0
	v_mov_b64_e32 v[124:125], 0
	v_mov_b64_e32 v[126:127], 0
	s_cbranch_vccnz .LBB0_918
	s_and_b64 s[58:59], s[58:59], exec
	s_cselect_b32 s1, s51, s55
	s_cselect_b32 s3, s50, s54
	s_add_u32 s54, s54, 0x40080
	s_addc_u32 s55, s55, 0
	s_add_u32 s43, s56, 0x100
	s_addc_u32 s45, s57, 0
	s_mov_b32 s47, 0

.LBB0_978:
	s_andn2_b64 vcc, exec, s[20:21]
	v_mov_b64_e32 v[0:1], 0
	v_mov_b64_e32 v[2:3], 0
	v_mov_b64_e32 v[4:5], 0
	v_mov_b64_e32 v[6:7], 0
	v_mov_b64_e32 v[8:9], 0
	v_mov_b64_e32 v[10:11], 0
	v_mov_b64_e32 v[12:13], 0
	v_mov_b64_e32 v[14:15], 0
	v_mov_b64_e32 v[16:17], 0
	v_mov_b64_e32 v[18:19], 0
	v_mov_b64_e32 v[20:21], 0
	v_mov_b64_e32 v[22:23], 0
	v_mov_b64_e32 v[24:25], 0
	v_mov_b64_e32 v[26:27], 0
	v_mov_b64_e32 v[28:29], 0
	v_mov_b64_e32 v[30:31], 0
	v_mov_b64_e32 v[32:33], 0
	v_mov_b64_e32 v[34:35], 0
	v_mov_b64_e32 v[36:37], 0
	v_mov_b64_e32 v[38:39], 0
	v_mov_b64_e32 v[40:41], 0
	v_mov_b64_e32 v[42:43], 0
	v_mov_b64_e32 v[44:45], 0
	v_mov_b64_e32 v[46:47], 0
	v_mov_b64_e32 v[48:49], 0
	v_mov_b64_e32 v[50:51], 0
	v_mov_b64_e32 v[52:53], 0
	v_mov_b64_e32 v[54:55], 0
	v_mov_b64_e32 v[56:57], 0
	v_mov_b64_e32 v[58:59], 0
	v_mov_b64_e32 v[60:61], 0
	v_mov_b64_e32 v[62:63], 0
	v_mov_b64_e32 v[64:65], 0
	v_mov_b64_e32 v[66:67], 0
	v_mov_b64_e32 v[68:69], 0
	v_mov_b64_e32 v[70:71], 0
	v_mov_b64_e32 v[72:73], 0
	v_mov_b64_e32 v[74:75], 0
	v_mov_b64_e32 v[76:77], 0
	v_mov_b64_e32 v[78:79], 0
	v_mov_b64_e32 v[80:81], 0
	v_mov_b64_e32 v[82:83], 0
	v_mov_b64_e32 v[84:85], 0
	v_mov_b64_e32 v[86:87], 0
	v_mov_b64_e32 v[88:89], 0
	v_mov_b64_e32 v[90:91], 0
	v_mov_b64_e32 v[92:93], 0
	v_mov_b64_e32 v[94:95], 0
	v_mov_b64_e32 v[96:97], 0
	v_mov_b64_e32 v[98:99], 0
	v_mov_b64_e32 v[100:101], 0
	v_mov_b64_e32 v[102:103], 0
	v_mov_b64_e32 v[104:105], 0
	v_mov_b64_e32 v[106:107], 0
	v_mov_b64_e32 v[108:109], 0
	v_mov_b64_e32 v[110:111], 0
	v_mov_b64_e32 v[112:113], 0
	v_mov_b64_e32 v[114:115], 0
	v_mov_b64_e32 v[116:117], 0
	v_mov_b64_e32 v[118:119], 0
	v_mov_b64_e32 v[120:121], 0
	v_mov_b64_e32 v[122:123], 0
	v_mov_b64_e32 v[124:125], 0
	v_mov_b64_e32 v[126:127], 0
	s_cbranch_vccnz .LBB0_982
	s_add_u32 s50, s50, 0x40080
	s_addc_u32 s51, s51, 0
	s_add_u32 s1, s52, 0x100
	s_addc_u32 s3, s53, 0
	s_mov_b32 s41, 0

.LBB0_1030:
	s_ashr_i32 s41, s40, 31
	s_lshl_b64 s[2:3], s[40:41], 19
	v_readlane_b32 s44, v254, 43
	v_readlane_b32 s45, v254, 44
	s_add_u32 s2, s44, s2
	s_addc_u32 s3, s45, s3
	s_ashr_i32 s43, s42, 31
	s_lshl_b64 s[44:45], s[42:43], 19
	v_readlane_b32 s1, v254, 41
	s_add_u32 s44, s1, s44
	v_readlane_b32 s1, v254, 42
	s_addc_u32 s45, s1, s45
	s_andn2_b64 vcc, exec, s[22:23]
	v_mov_b64_e32 v[0:1], 0
	v_mov_b64_e32 v[2:3], 0
	v_mov_b64_e32 v[4:5], 0
	v_mov_b64_e32 v[6:7], 0
	v_mov_b64_e32 v[8:9], 0
	v_mov_b64_e32 v[10:11], 0
	v_mov_b64_e32 v[12:13], 0
	v_mov_b64_e32 v[14:15], 0
	v_mov_b64_e32 v[16:17], 0
	v_mov_b64_e32 v[18:19], 0
	v_mov_b64_e32 v[20:21], 0
	v_mov_b64_e32 v[22:23], 0
	v_mov_b64_e32 v[24:25], 0
	v_mov_b64_e32 v[26:27], 0
	v_mov_b64_e32 v[28:29], 0
	v_mov_b64_e32 v[30:31], 0
	v_mov_b64_e32 v[32:33], 0
	v_mov_b64_e32 v[34:35], 0
	v_mov_b64_e32 v[36:37], 0
	v_mov_b64_e32 v[38:39], 0
	v_mov_b64_e32 v[40:41], 0
	v_mov_b64_e32 v[42:43], 0
	v_mov_b64_e32 v[44:45], 0
	v_mov_b64_e32 v[46:47], 0
	v_mov_b64_e32 v[48:49], 0
	v_mov_b64_e32 v[50:51], 0
	v_mov_b64_e32 v[52:53], 0
	v_mov_b64_e32 v[54:55], 0
	v_mov_b64_e32 v[56:57], 0
	v_mov_b64_e32 v[58:59], 0
	v_mov_b64_e32 v[60:61], 0
	v_mov_b64_e32 v[62:63], 0
	v_mov_b64_e32 v[64:65], 0
	v_mov_b64_e32 v[66:67], 0
	v_mov_b64_e32 v[68:69], 0
	v_mov_b64_e32 v[70:71], 0
	v_mov_b64_e32 v[72:73], 0
	v_mov_b64_e32 v[74:75], 0
	v_mov_b64_e32 v[76:77], 0
	v_mov_b64_e32 v[78:79], 0
	v_mov_b64_e32 v[80:81], 0
	v_mov_b64_e32 v[82:83], 0
	v_mov_b64_e32 v[84:85], 0
	v_mov_b64_e32 v[86:87], 0
	v_mov_b64_e32 v[88:89], 0
	v_mov_b64_e32 v[90:91], 0
	v_mov_b64_e32 v[92:93], 0
	v_mov_b64_e32 v[94:95], 0
	v_mov_b64_e32 v[96:97], 0
	v_mov_b64_e32 v[98:99], 0
	v_mov_b64_e32 v[100:101], 0
	v_mov_b64_e32 v[102:103], 0
	v_mov_b64_e32 v[104:105], 0
	v_mov_b64_e32 v[106:107], 0
	v_mov_b64_e32 v[108:109], 0
	v_mov_b64_e32 v[110:111], 0
	v_mov_b64_e32 v[112:113], 0
	v_mov_b64_e32 v[114:115], 0
	v_mov_b64_e32 v[116:117], 0
	v_mov_b64_e32 v[118:119], 0
	v_mov_b64_e32 v[120:121], 0
	v_mov_b64_e32 v[122:123], 0
	v_mov_b64_e32 v[124:125], 0
	v_mov_b64_e32 v[126:127], 0
	s_cbranch_vccnz .LBB0_1033
	s_and_b64 s[52:53], s[38:39], exec
	s_cselect_b32 s1, s3, s49
	s_cselect_b32 s41, s2, s48
	s_cselect_b32 s43, s45, s51
	s_cselect_b32 s47, s44, s50
	s_add_u32 s48, s48, 0x40080
	s_addc_u32 s49, s49, 0
	s_add_u32 s67, s50, 0x100
	s_addc_u32 s68, s51, 0
	s_mov_b32 s50, 0
